# v88 + RELU2 GEMM epilogue (phases 6, 13): bf16 8-byte stores widened to 16-byte stores via v_permlane16_swap row exchange (same bytes, same addresses)
# speedup vs baseline: 1.0087x; 1.0087x over previous
.LBB0_564:
	s_mul_i32 s51, s45, 0x6000
	s_add_i32 s52, s51, 0xffffa000
	s_cmp_lg_u32 s45, 0
	s_cselect_b32 s52, s52, 0xc000
	v_add_u32_e32 v146, s52, v138
	v_lshl_add_u64 v[142:143], v[134:135], 0, s[48:49]
	v_readfirstlane_b32 s52, v146
	v_add_u32_e32 v147, 0x1000, v146
	v_lshl_add_u64 v[144:145], v[142:143], 0, s[22:23]
	s_mov_b32 m0, s52
	v_readfirstlane_b32 s52, v147
	v_add_u32_e32 v147, 0x2000, v146
	s_waitcnt vmcnt(6)
	s_barrier
	global_load_lds_dwordx4 v[144:145], off
	v_lshl_add_u64 v[144:145], v[142:143], 0, s[24:25]
	s_mov_b32 m0, s52
	v_readfirstlane_b32 s52, v147
	global_load_lds_dwordx4 v[144:145], off
	v_lshl_add_u64 v[144:145], v[142:143], 0, s[26:27]
	s_mov_b32 m0, s52
	v_lshl_add_u64 v[142:143], v[142:143], 0, s[28:29]
	global_load_lds_dwordx4 v[144:145], off
	v_add_u32_e32 v144, 0x3000, v146
	v_add_u32_e32 v147, 0x4000, v146
	v_readfirstlane_b32 s52, v144
	s_mov_b32 m0, s52
	v_readfirstlane_b32 s52, v147
	global_load_lds_dwordx4 v[142:143], off
	v_lshl_add_u64 v[142:143], v[132:133], 0, s[48:49]
	v_lshl_add_u64 v[144:145], v[142:143], 0, s[30:31]
	s_mov_b32 m0, s52
	v_lshl_add_u64 v[142:143], v[142:143], 0, s[34:35]
	global_load_lds_dwordx4 v[144:145], off
	v_add_u32_e32 v144, 0x5000, v146
	s_add_i32 s51, s51, 0
	v_readfirstlane_b32 s52, v144
	s_mov_b32 m0, s52
	v_add3_u32 v154, s51, v139, v141
	global_load_lds_dwordx4 v[142:143], off
	v_add3_u32 v174, s51, v140, v141
	ds_read_b128 v[142:145], v154 offset:16384
	ds_read_b128 v[146:149], v154 offset:17408
	ds_read_b128 v[150:153], v154 offset:18432
	ds_read_b128 v[154:157], v154 offset:19456
	ds_read_b128 v[158:161], v174
	ds_read_b128 v[162:165], v174 offset:1024
	ds_read_b128 v[166:169], v174 offset:2048
	ds_read_b128 v[170:173], v174 offset:3072
	s_setprio 1
	s_waitcnt lgkmcnt(0)
	v_mfma_f32_16x16x32_bf16 v[126:129], v[142:145], v[158:161], v[126:129]
	v_mfma_f32_16x16x32_bf16 v[122:125], v[146:149], v[158:161], v[122:125]
	v_mfma_f32_16x16x32_bf16 v[118:121], v[150:153], v[158:161], v[118:121]
	v_mfma_f32_16x16x32_bf16 v[114:117], v[154:157], v[158:161], v[114:117]
	v_mfma_f32_16x16x32_bf16 v[110:113], v[142:145], v[162:165], v[110:113]
	v_mfma_f32_16x16x32_bf16 v[106:109], v[146:149], v[162:165], v[106:109]
	v_mfma_f32_16x16x32_bf16 v[102:105], v[150:153], v[162:165], v[102:105]
	v_mfma_f32_16x16x32_bf16 v[98:101], v[154:157], v[162:165], v[98:101]
	v_mfma_f32_16x16x32_bf16 v[94:97], v[142:145], v[166:169], v[94:97]
	v_mfma_f32_16x16x32_bf16 v[90:93], v[146:149], v[166:169], v[90:93]
	v_mfma_f32_16x16x32_bf16 v[86:89], v[150:153], v[166:169], v[86:89]
	v_mfma_f32_16x16x32_bf16 v[82:85], v[154:157], v[166:169], v[82:85]
	v_mfma_f32_16x16x32_bf16 v[78:81], v[142:145], v[170:173], v[78:81]
	v_mfma_f32_16x16x32_bf16 v[74:77], v[146:149], v[170:173], v[74:77]
	v_mfma_f32_16x16x32_bf16 v[70:73], v[150:153], v[170:173], v[70:73]
	v_mfma_f32_16x16x32_bf16 v[66:69], v[154:157], v[170:173], v[66:69]
	s_setprio 0
	ds_read_b128 v[158:161], v174 offset:4096
	ds_read_b128 v[162:165], v174 offset:5120
	ds_read_b128 v[166:169], v174 offset:6144
	ds_read_b128 v[170:173], v174 offset:7168
	s_setprio 1
	s_waitcnt lgkmcnt(0)
	v_mfma_f32_16x16x32_bf16 v[62:65], v[142:145], v[158:161], v[62:65]
	v_mfma_f32_16x16x32_bf16 v[58:61], v[146:149], v[158:161], v[58:61]
	v_mfma_f32_16x16x32_bf16 v[54:57], v[150:153], v[158:161], v[54:57]
	v_mfma_f32_16x16x32_bf16 v[50:53], v[154:157], v[158:161], v[50:53]
	v_mfma_f32_16x16x32_bf16 v[46:49], v[142:145], v[162:165], v[46:49]
	v_mfma_f32_16x16x32_bf16 v[42:45], v[146:149], v[162:165], v[42:45]
	v_mfma_f32_16x16x32_bf16 v[38:41], v[150:153], v[162:165], v[38:41]
	v_mfma_f32_16x16x32_bf16 v[34:37], v[154:157], v[162:165], v[34:37]
	v_mfma_f32_16x16x32_bf16 v[30:33], v[142:145], v[166:169], v[30:33]
	v_mfma_f32_16x16x32_bf16 v[26:29], v[146:149], v[166:169], v[26:29]
	v_mfma_f32_16x16x32_bf16 v[22:25], v[150:153], v[166:169], v[22:25]
	v_mfma_f32_16x16x32_bf16 v[18:21], v[154:157], v[166:169], v[18:21]
	v_mfma_f32_16x16x32_bf16 v[14:17], v[142:145], v[170:173], v[14:17]
	v_mfma_f32_16x16x32_bf16 v[10:13], v[146:149], v[170:173], v[10:13]
	v_mfma_f32_16x16x32_bf16 v[6:9], v[150:153], v[170:173], v[6:9]
	v_mfma_f32_16x16x32_bf16 v[2:5], v[154:157], v[170:173], v[2:5]
	s_setprio 0
	s_add_i32 s51, s45, 1
	s_cmp_lg_u32 s45, 2
	s_cselect_b32 s45, s51, 0
	s_add_u32 s48, s48, 64
	s_addc_u32 s49, s49, 0
	s_cmpk_eq_i32 s48, 0x780
	s_cbranch_scc0 .LBB0_564
	v_add3_u32 v166, 0, v139, v141
	v_add3_u32 v167, 0, v140, v141
	s_waitcnt vmcnt(6)
	s_barrier
	ds_read_b128 v[132:135], v166 offset:16384
	ds_read_b128 v[142:145], v166 offset:17408
	ds_read_b128 v[146:149], v166 offset:18432
	ds_read_b128 v[150:153], v166 offset:19456
	ds_read_b128 v[138:141], v167
	ds_read_b128 v[154:157], v167 offset:1024
	ds_read_b128 v[158:161], v167 offset:2048
	ds_read_b128 v[162:165], v167 offset:3072
	s_setprio 1
	s_waitcnt lgkmcnt(0)
	v_mfma_f32_16x16x32_bf16 v[126:129], v[132:135], v[138:141], v[126:129]
	v_mfma_f32_16x16x32_bf16 v[122:125], v[142:145], v[138:141], v[122:125]
	v_mfma_f32_16x16x32_bf16 v[118:121], v[146:149], v[138:141], v[118:121]
	v_mfma_f32_16x16x32_bf16 v[114:117], v[150:153], v[138:141], v[114:117]
	v_mfma_f32_16x16x32_bf16 v[110:113], v[132:135], v[154:157], v[110:113]
	v_mfma_f32_16x16x32_bf16 v[106:109], v[142:145], v[154:157], v[106:109]
	v_mfma_f32_16x16x32_bf16 v[102:105], v[146:149], v[154:157], v[102:105]
	v_mfma_f32_16x16x32_bf16 v[98:101], v[150:153], v[154:157], v[98:101]
	v_mfma_f32_16x16x32_bf16 v[94:97], v[132:135], v[158:161], v[94:97]
	v_mfma_f32_16x16x32_bf16 v[90:93], v[142:145], v[158:161], v[90:93]
	v_mfma_f32_16x16x32_bf16 v[86:89], v[146:149], v[158:161], v[86:89]
	v_mfma_f32_16x16x32_bf16 v[82:85], v[150:153], v[158:161], v[82:85]
	v_mfma_f32_16x16x32_bf16 v[78:81], v[132:135], v[162:165], v[78:81]
	v_mfma_f32_16x16x32_bf16 v[74:77], v[142:145], v[162:165], v[74:77]
	v_mfma_f32_16x16x32_bf16 v[70:73], v[146:149], v[162:165], v[70:73]
	v_mfma_f32_16x16x32_bf16 v[66:69], v[150:153], v[162:165], v[66:69]
	s_setprio 0
	ds_read_b128 v[138:141], v167 offset:4096
	ds_read_b128 v[154:157], v167 offset:5120
	ds_read_b128 v[158:161], v167 offset:6144
	ds_read_b128 v[162:165], v167 offset:7168
	s_setprio 1
	s_waitcnt lgkmcnt(0)
	v_mfma_f32_16x16x32_bf16 v[62:65], v[132:135], v[138:141], v[62:65]
	v_mfma_f32_16x16x32_bf16 v[58:61], v[142:145], v[138:141], v[58:61]
	v_mfma_f32_16x16x32_bf16 v[54:57], v[146:149], v[138:141], v[54:57]
	v_mfma_f32_16x16x32_bf16 v[50:53], v[150:153], v[138:141], v[50:53]
	v_mfma_f32_16x16x32_bf16 v[46:49], v[132:135], v[154:157], v[46:49]
	v_mfma_f32_16x16x32_bf16 v[42:45], v[142:145], v[154:157], v[42:45]
	v_mfma_f32_16x16x32_bf16 v[38:41], v[146:149], v[154:157], v[38:41]
	v_mfma_f32_16x16x32_bf16 v[34:37], v[150:153], v[154:157], v[34:37]
	v_mfma_f32_16x16x32_bf16 v[30:33], v[132:135], v[158:161], v[30:33]
	v_mfma_f32_16x16x32_bf16 v[26:29], v[142:145], v[158:161], v[26:29]
	v_mfma_f32_16x16x32_bf16 v[22:25], v[146:149], v[158:161], v[22:25]
	v_mfma_f32_16x16x32_bf16 v[18:21], v[150:153], v[158:161], v[18:21]
	v_mfma_f32_16x16x32_bf16 v[14:17], v[132:135], v[162:165], v[14:17]
	v_mfma_f32_16x16x32_bf16 v[10:13], v[142:145], v[162:165], v[10:13]
	v_mfma_f32_16x16x32_bf16 v[6:9], v[146:149], v[162:165], v[6:9]
	v_mfma_f32_16x16x32_bf16 v[2:5], v[150:153], v[162:165], v[2:5]
	s_setprio 0
	s_waitcnt vmcnt(0)
	s_barrier
	ds_read_b128 v[132:135], v166 offset:40960
	ds_read_b128 v[138:141], v166 offset:41984
	ds_read_b128 v[142:145], v166 offset:43008
	ds_read_b128 v[146:149], v166 offset:44032
	ds_read_b128 v[150:153], v167 offset:24576
	ds_read_b128 v[154:157], v167 offset:25600
	ds_read_b128 v[158:161], v167 offset:26624
	ds_read_b128 v[162:165], v167 offset:27648
	s_lshl_b64 s[46:47], s[46:47], 8
	s_setprio 1
	s_waitcnt lgkmcnt(0)
	v_mfma_f32_16x16x32_bf16 v[126:129], v[132:135], v[150:153], v[126:129]
	v_mfma_f32_16x16x32_bf16 v[122:125], v[138:141], v[150:153], v[122:125]
	v_mfma_f32_16x16x32_bf16 v[118:121], v[142:145], v[150:153], v[118:121]
	v_mfma_f32_16x16x32_bf16 v[114:117], v[146:149], v[150:153], v[114:117]
	v_mfma_f32_16x16x32_bf16 v[110:113], v[132:135], v[154:157], v[110:113]
	v_mfma_f32_16x16x32_bf16 v[150:153], v[138:141], v[154:157], v[106:109]
	v_mfma_f32_16x16x32_bf16 v[102:105], v[142:145], v[154:157], v[102:105]
	v_mfma_f32_16x16x32_bf16 v[98:101], v[146:149], v[154:157], v[98:101]
	v_mfma_f32_16x16x32_bf16 v[94:97], v[132:135], v[158:161], v[94:97]
	v_mfma_f32_16x16x32_bf16 v[90:93], v[138:141], v[158:161], v[90:93]
	v_mfma_f32_16x16x32_bf16 v[86:89], v[142:145], v[158:161], v[86:89]
	v_mfma_f32_16x16x32_bf16 v[82:85], v[146:149], v[158:161], v[82:85]
	v_mfma_f32_16x16x32_bf16 v[78:81], v[132:135], v[162:165], v[78:81]
	v_mfma_f32_16x16x32_bf16 v[74:77], v[138:141], v[162:165], v[74:77]
	v_mfma_f32_16x16x32_bf16 v[70:73], v[142:145], v[162:165], v[70:73]
	v_mfma_f32_16x16x32_bf16 v[66:69], v[146:149], v[162:165], v[66:69]
	s_setprio 0
	ds_read_b128 v[106:109], v167 offset:28672
	ds_read_b128 v[154:157], v167 offset:29696
	ds_read_b128 v[158:161], v167 offset:30720
	ds_read_b128 v[162:165], v167 offset:31744
	s_setprio 1
	s_waitcnt lgkmcnt(0)
	v_mfma_f32_16x16x32_bf16 v[62:65], v[132:135], v[106:109], v[62:65]
	v_mfma_f32_16x16x32_bf16 v[58:61], v[138:141], v[106:109], v[58:61]
	v_mfma_f32_16x16x32_bf16 v[54:57], v[142:145], v[106:109], v[54:57]
	v_mfma_f32_16x16x32_bf16 v[50:53], v[146:149], v[106:109], v[50:53]
	v_mfma_f32_16x16x32_bf16 v[46:49], v[132:135], v[154:157], v[46:49]
	v_mfma_f32_16x16x32_bf16 v[42:45], v[138:141], v[154:157], v[42:45]
	v_mfma_f32_16x16x32_bf16 v[38:41], v[142:145], v[154:157], v[38:41]
	v_mfma_f32_16x16x32_bf16 v[34:37], v[146:149], v[154:157], v[34:37]
	v_mfma_f32_16x16x32_bf16 v[30:33], v[132:135], v[158:161], v[30:33]
	v_mfma_f32_16x16x32_bf16 v[26:29], v[138:141], v[158:161], v[26:29]
	v_mfma_f32_16x16x32_bf16 v[22:25], v[142:145], v[158:161], v[22:25]
	v_mfma_f32_16x16x32_bf16 v[18:21], v[146:149], v[158:161], v[18:21]
	v_mfma_f32_16x16x32_bf16 v[14:17], v[132:135], v[162:165], v[14:17]
	v_mfma_f32_16x16x32_bf16 v[10:13], v[138:141], v[162:165], v[10:13]
	v_mfma_f32_16x16x32_bf16 v[6:9], v[142:145], v[162:165], v[6:9]
	v_mfma_f32_16x16x32_bf16 v[2:5], v[146:149], v[162:165], v[2:5]
	s_setprio 0
	v_lshl_add_u64 v[106:107], s[46:47], 0, v[130:131]
	v_lshl_add_u64 v[108:109], v[106:107], 2, s[8:9]
	s_waitcnt vmcnt(0)
	s_barrier
	flat_load_dword v138, v[108:109]
	v_max_f32_e32 v109, v126, v126
	v_max_f32_e32 v126, v127, v127
	v_max_f32_e32 v127, v128, v128
	v_max_f32_e32 v128, v129, v129
	v_max_f32_e32 v122, v122, v122
	v_max_f32_e32 v124, v124, v124
	v_max_f32_e32 v129, v118, v118
	v_max_f32_e32 v139, v115, v115
	v_max_f32_e32 v133, v120, v120
	v_max_f32_e32 v120, 0, v122
	v_max_f32_e32 v122, 0, v124
	v_max_f32_e32 v124, 0, v129
	v_max_f32_e32 v129, 0, v139
	v_max_f32_e32 v123, v123, v123
	v_max_f32_e32 v125, v125, v125
	v_max_f32_e32 v132, v119, v119
	v_max_f32_e32 v140, v116, v116
	v_max_f32_e32 v134, v121, v121
	v_max_f32_e32 v121, 0, v123
	v_max_f32_e32 v123, 0, v125
	v_max_f32_e32 v125, 0, v132
	v_max_f32_e32 v132, 0, v140
	v_max_f32_e32 v141, v117, v117
	v_max_f32_e32 v117, 0, v126
	v_max_f32_e32 v126, 0, v133
	v_max_f32_e32 v133, 0, v141
	v_lshl_or_b32 v108, s44, 7, v136
	v_max_f32_e32 v135, v114, v114
	v_max_f32_e32 v116, 0, v109
	v_max_f32_e32 v118, 0, v127
	v_max_f32_e32 v119, 0, v128
	v_lshlrev_b64 v[114:115], 13, v[106:107]
	v_ashrrev_i32_e32 v109, 31, v108
	v_max_f32_e32 v127, 0, v134
	v_max_f32_e32 v128, 0, v135
	v_lshl_add_u64 v[114:115], s[6:7], 0, v[114:115]
	v_lshlrev_b64 v[108:109], 1, v[108:109]
	v_or_b32_e32 v134, 16, v106
	v_mov_b32_e32 v135, v107
	v_lshl_add_u64 v[114:115], v[114:115], 0, v[108:109]
	v_max_f32_e32 v110, v110, v110
	v_max_f32_e32 v111, v111, v111
	v_max_f32_e32 v112, v112, v112
	v_max_f32_e32 v113, v113, v113
	v_max_f32_e32 v94, v94, v94
	v_max_f32_e32 v95, v95, v95
	v_max_f32_e32 v96, v96, v96
	v_max_f32_e32 v97, v97, v97
	v_max_f32_e32 v90, v90, v90
	v_max_f32_e32 v91, v91, v91
	v_max_f32_e32 v92, v92, v92
	v_max_f32_e32 v93, v93, v93
	v_max_f32_e32 v78, v78, v78
	v_max_f32_e32 v79, v79, v79
	v_max_f32_e32 v80, v80, v80
	v_max_f32_e32 v81, v81, v81
	v_max_f32_e32 v74, v74, v74
	v_max_f32_e32 v75, v75, v75
	v_max_f32_e32 v76, v76, v76
	v_max_f32_e32 v77, v77, v77
	v_max_f32_e32 v62, v62, v62
	v_max_f32_e32 v63, v63, v63
	v_max_f32_e32 v64, v64, v64
	v_max_f32_e32 v65, v65, v65
	v_max_f32_e32 v58, v58, v58
	v_max_f32_e32 v59, v59, v59
	v_max_f32_e32 v60, v60, v60
	v_max_f32_e32 v61, v61, v61
	v_max_f32_e32 v46, v46, v46
	v_max_f32_e32 v47, v47, v47
	v_max_f32_e32 v48, v48, v48
	v_max_f32_e32 v49, v49, v49
	v_max_f32_e32 v42, v42, v42
	v_max_f32_e32 v43, v43, v43
	v_max_f32_e32 v44, v44, v44
	v_max_f32_e32 v45, v45, v45
	v_max_f32_e32 v28, v28, v28
	v_max_f32_e32 v29, v29, v29
	v_max_f32_e32 v30, v30, v30
	s_waitcnt vmcnt(0) lgkmcnt(0)
	v_fmamk_f32 v138, v138, 0x3a800000, v137
	v_mul_f32_e32 v139, 0x4b800000, v138
	v_cmp_gt_f32_e32 vcc, s43, v138
	v_max_f32_e32 v31, v31, v31
	v_max_f32_e32 v32, v32, v32
	v_cndmask_b32_e32 v138, v138, v139, vcc
	v_rsq_f32_e32 v140, v138
	v_lshl_add_u64 v[138:139], v[134:135], 2, s[8:9]
	v_max_f32_e32 v33, v33, v33
	v_max_f32_e32 v26, v26, v26
	v_mul_f32_e32 v141, 0x45800000, v140
	v_cndmask_b32_e32 v140, v140, v141, vcc
	v_pk_mul_f32 v[116:117], v[116:117], v[140:141] op_sel_hi:[1,0]
	v_pk_mul_f32 v[118:119], v[118:119], v[140:141] op_sel_hi:[1,0]
	v_pk_mul_f32 v[120:121], v[120:121], v[140:141] op_sel_hi:[1,0]
	v_pk_mul_f32 v[122:123], v[122:123], v[140:141] op_sel_hi:[1,0]
	v_pk_mul_f32 v[124:125], v[124:125], v[140:141] op_sel_hi:[1,0]
	v_pk_mul_f32 v[126:127], v[126:127], v[140:141] op_sel_hi:[1,0]
	v_pk_mul_f32 v[128:129], v[128:129], v[140:141] op_sel_hi:[1,0]
	v_pk_mul_f32 v[132:133], v[132:133], v[140:141] op_sel_hi:[1,0]
	v_pk_mul_f32 v[116:117], v[116:117], v[116:117]
	v_pk_mul_f32 v[118:119], v[118:119], v[118:119]
	v_pk_mul_f32 v[120:121], v[120:121], v[120:121]
	v_pk_mul_f32 v[122:123], v[122:123], v[122:123]
	v_pk_mul_f32 v[124:125], v[124:125], v[124:125]
	v_pk_mul_f32 v[126:127], v[126:127], v[126:127]
	v_pk_mul_f32 v[128:129], v[128:129], v[128:129]
	v_pk_mul_f32 v[132:133], v[132:133], v[132:133]
	v_cvt_pk_bf16_f32 v116, v116, v117
	v_cvt_pk_bf16_f32 v117, v118, v119
	v_cvt_pk_bf16_f32 v118, v120, v121
	v_cvt_pk_bf16_f32 v119, v122, v123
	v_cvt_pk_bf16_f32 v120, v124, v125
	v_cvt_pk_bf16_f32 v121, v126, v127
	v_cvt_pk_bf16_f32 v122, v128, v129
	v_cvt_pk_bf16_f32 v123, v132, v133
	v_mbcnt_lo_u32_b32 v242, -1, 0
	v_mbcnt_hi_u32_b32 v242, -1, v242
	v_and_b32_e32 v242, 16, v242
	v_lshrrev_b32_e32 v240, 1, v242
	v_add_u32_e32 v242, v242, v240
	v_mov_b32_e32 v243, 0
	v_lshl_add_u64 v[240:241], v[114:115], 0, v[242:243]
	v_permlane16_swap_b32_e32 v116, v118
	v_permlane16_swap_b32_e32 v117, v119
	v_permlane16_swap_b32_e32 v120, v122
	v_permlane16_swap_b32_e32 v121, v123
	global_store_dwordx4 v[240:241], v[116:119], off
	global_store_dwordx4 v[240:241], v[120:123], off offset:64
	s_nop 1
	flat_load_dword v122, v[138:139]
	v_max_f32_e32 v114, v150, v150
	v_max_f32_e32 v123, v98, v98
	v_max_f32_e32 v118, v102, v102
	v_max_f32_e32 v102, 0, v114
	v_max_f32_e32 v114, 0, v123
	v_max_f32_e32 v115, v151, v151
	v_max_f32_e32 v124, v99, v99
	v_max_f32_e32 v119, v103, v103
	v_max_f32_e32 v103, 0, v115
	v_max_f32_e32 v115, 0, v124
	v_max_f32_e32 v116, v152, v152
	v_max_f32_e32 v125, v100, v100
	v_max_f32_e32 v120, v104, v104
	v_max_f32_e32 v104, 0, v116
	v_max_f32_e32 v116, 0, v125
	v_max_f32_e32 v117, v153, v153
	v_max_f32_e32 v121, v105, v105
	v_max_f32_e32 v126, v101, v101
	v_max_f32_e32 v98, 0, v110
	v_max_f32_e32 v99, 0, v111
	v_max_f32_e32 v100, 0, v112
	v_max_f32_e32 v101, 0, v113
	v_max_f32_e32 v105, 0, v117
	v_max_f32_e32 v110, 0, v118
	v_max_f32_e32 v111, 0, v119
	v_max_f32_e32 v112, 0, v120
	v_max_f32_e32 v113, 0, v121
	v_max_f32_e32 v117, 0, v126
	v_lshlrev_b64 v[120:121], 13, v[134:135]
	v_lshl_add_u64 v[120:121], s[6:7], 0, v[120:121]
	v_or_b32_e32 v118, 32, v106
	v_mov_b32_e32 v119, v107
	v_lshl_add_u64 v[120:121], v[120:121], 0, v[108:109]
	v_max_f32_e32 v27, v27, v27
	v_max_f32_e32 v10, v10, v10
	v_max_f32_e32 v11, v11, v11
	v_max_f32_e32 v12, v12, v12
	v_max_f32_e32 v14, v14, v14
	v_max_f32_e32 v15, v15, v15
	v_max_f32_e32 v16, v16, v16
	v_max_f32_e32 v17, v17, v17
	v_max_f32_e32 v13, v13, v13
	s_add_i32 s50, s50, s40
	s_cmpk_gt_i32 s50, 0x1fff
	s_waitcnt vmcnt(0) lgkmcnt(0)
	v_fmamk_f32 v122, v122, 0x3a800000, v137
	v_mul_f32_e32 v123, 0x4b800000, v122
	v_cmp_gt_f32_e32 vcc, s43, v122
	s_nop 1
	v_cndmask_b32_e32 v122, v122, v123, vcc
	v_rsq_f32_e32 v124, v122
	v_lshl_add_u64 v[122:123], v[118:119], 2, s[8:9]
	v_mul_f32_e32 v125, 0x45800000, v124
	v_cndmask_b32_e32 v124, v124, v125, vcc
	v_pk_mul_f32 v[98:99], v[98:99], v[124:125] op_sel_hi:[1,0]
	v_pk_mul_f32 v[100:101], v[100:101], v[124:125] op_sel_hi:[1,0]
	v_pk_mul_f32 v[102:103], v[102:103], v[124:125] op_sel_hi:[1,0]
	v_pk_mul_f32 v[104:105], v[104:105], v[124:125] op_sel_hi:[1,0]
	v_pk_mul_f32 v[110:111], v[110:111], v[124:125] op_sel_hi:[1,0]
	v_pk_mul_f32 v[112:113], v[112:113], v[124:125] op_sel_hi:[1,0]
	v_pk_mul_f32 v[114:115], v[114:115], v[124:125] op_sel_hi:[1,0]
	v_pk_mul_f32 v[116:117], v[116:117], v[124:125] op_sel_hi:[1,0]
	v_pk_mul_f32 v[98:99], v[98:99], v[98:99]
	v_pk_mul_f32 v[100:101], v[100:101], v[100:101]
	v_pk_mul_f32 v[102:103], v[102:103], v[102:103]
	v_pk_mul_f32 v[104:105], v[104:105], v[104:105]
	v_pk_mul_f32 v[110:111], v[110:111], v[110:111]
	v_pk_mul_f32 v[112:113], v[112:113], v[112:113]
	v_pk_mul_f32 v[114:115], v[114:115], v[114:115]
	v_pk_mul_f32 v[116:117], v[116:117], v[116:117]
	v_cvt_pk_bf16_f32 v98, v98, v99
	v_cvt_pk_bf16_f32 v99, v100, v101
	v_cvt_pk_bf16_f32 v100, v102, v103
	v_cvt_pk_bf16_f32 v101, v104, v105
	v_cvt_pk_bf16_f32 v102, v110, v111
	v_cvt_pk_bf16_f32 v103, v112, v113
	v_cvt_pk_bf16_f32 v104, v114, v115
	v_cvt_pk_bf16_f32 v105, v116, v117
	v_mbcnt_lo_u32_b32 v242, -1, 0
	v_mbcnt_hi_u32_b32 v242, -1, v242
	v_and_b32_e32 v242, 16, v242
	v_lshrrev_b32_e32 v240, 1, v242
	v_add_u32_e32 v242, v242, v240
	v_mov_b32_e32 v243, 0
	v_lshl_add_u64 v[240:241], v[120:121], 0, v[242:243]
	v_permlane16_swap_b32_e32 v98, v100
	v_permlane16_swap_b32_e32 v99, v101
	v_permlane16_swap_b32_e32 v102, v104
	v_permlane16_swap_b32_e32 v103, v105
	global_store_dwordx4 v[240:241], v[98:101], off
	global_store_dwordx4 v[240:241], v[102:105], off offset:64
	s_nop 1
	flat_load_dword v102, v[122:123]
	v_max_f32_e32 v103, v82, v82
	v_max_f32_e32 v82, 0, v94
	v_max_f32_e32 v94, 0, v103
	v_max_f32_e32 v104, v83, v83
	v_max_f32_e32 v83, 0, v95
	v_max_f32_e32 v95, 0, v104
	v_max_f32_e32 v105, v84, v84
	v_max_f32_e32 v84, 0, v96
	v_max_f32_e32 v96, 0, v105
	v_max_f32_e32 v98, v86, v86
	v_max_f32_e32 v99, v87, v87
	v_max_f32_e32 v100, v88, v88
	v_max_f32_e32 v101, v89, v89
	v_max_f32_e32 v110, v85, v85
	v_max_f32_e32 v85, 0, v97
	v_max_f32_e32 v86, 0, v90
	v_max_f32_e32 v87, 0, v91
	v_max_f32_e32 v88, 0, v92
	v_max_f32_e32 v89, 0, v93
	v_max_f32_e32 v90, 0, v98
	v_max_f32_e32 v91, 0, v99
	v_max_f32_e32 v92, 0, v100
	v_max_f32_e32 v93, 0, v101
	v_max_f32_e32 v97, 0, v110
	v_lshlrev_b64 v[100:101], 13, v[118:119]
	v_lshl_add_u64 v[100:101], s[6:7], 0, v[100:101]
	v_or_b32_e32 v98, 48, v106
	v_mov_b32_e32 v99, v107
	v_lshl_add_u64 v[100:101], v[100:101], 0, v[108:109]
	s_waitcnt vmcnt(0) lgkmcnt(0)
	v_fmamk_f32 v102, v102, 0x3a800000, v137
	v_mul_f32_e32 v103, 0x4b800000, v102
	v_cmp_gt_f32_e32 vcc, s43, v102
	s_nop 1
	v_cndmask_b32_e32 v102, v102, v103, vcc
	v_rsq_f32_e32 v104, v102
	v_lshl_add_u64 v[102:103], v[98:99], 2, s[8:9]
	v_mul_f32_e32 v105, 0x45800000, v104
	v_cndmask_b32_e32 v104, v104, v105, vcc
	v_pk_mul_f32 v[82:83], v[82:83], v[104:105] op_sel_hi:[1,0]
	v_pk_mul_f32 v[84:85], v[84:85], v[104:105] op_sel_hi:[1,0]
	v_pk_mul_f32 v[86:87], v[86:87], v[104:105] op_sel_hi:[1,0]
	v_pk_mul_f32 v[88:89], v[88:89], v[104:105] op_sel_hi:[1,0]
	v_pk_mul_f32 v[90:91], v[90:91], v[104:105] op_sel_hi:[1,0]
	v_pk_mul_f32 v[92:93], v[92:93], v[104:105] op_sel_hi:[1,0]
	v_pk_mul_f32 v[94:95], v[94:95], v[104:105] op_sel_hi:[1,0]
	v_pk_mul_f32 v[96:97], v[96:97], v[104:105] op_sel_hi:[1,0]
	v_pk_mul_f32 v[82:83], v[82:83], v[82:83]
	v_pk_mul_f32 v[84:85], v[84:85], v[84:85]
	v_pk_mul_f32 v[86:87], v[86:87], v[86:87]
	v_pk_mul_f32 v[88:89], v[88:89], v[88:89]
	v_pk_mul_f32 v[90:91], v[90:91], v[90:91]
	v_pk_mul_f32 v[92:93], v[92:93], v[92:93]
	v_pk_mul_f32 v[94:95], v[94:95], v[94:95]
	v_pk_mul_f32 v[96:97], v[96:97], v[96:97]
	v_cvt_pk_bf16_f32 v82, v82, v83
	v_cvt_pk_bf16_f32 v83, v84, v85
	v_cvt_pk_bf16_f32 v84, v86, v87
	v_cvt_pk_bf16_f32 v85, v88, v89
	v_cvt_pk_bf16_f32 v86, v90, v91
	v_cvt_pk_bf16_f32 v87, v92, v93
	v_cvt_pk_bf16_f32 v88, v94, v95
	v_cvt_pk_bf16_f32 v89, v96, v97
	v_mbcnt_lo_u32_b32 v242, -1, 0
	v_mbcnt_hi_u32_b32 v242, -1, v242
	v_and_b32_e32 v242, 16, v242
	v_lshrrev_b32_e32 v240, 1, v242
	v_add_u32_e32 v242, v242, v240
	v_mov_b32_e32 v243, 0
	v_lshl_add_u64 v[240:241], v[100:101], 0, v[242:243]
	v_permlane16_swap_b32_e32 v82, v84
	v_permlane16_swap_b32_e32 v83, v85
	v_permlane16_swap_b32_e32 v86, v88
	v_permlane16_swap_b32_e32 v87, v89
	global_store_dwordx4 v[240:241], v[82:85], off
	global_store_dwordx4 v[240:241], v[86:89], off offset:64
	s_nop 1
	flat_load_dword v86, v[102:103]
	v_max_f32_e32 v87, v66, v66
	v_max_f32_e32 v66, 0, v78
	v_max_f32_e32 v78, 0, v87
	v_max_f32_e32 v88, v67, v67
	v_max_f32_e32 v67, 0, v79
	v_max_f32_e32 v79, 0, v88
	v_max_f32_e32 v89, v68, v68
	v_max_f32_e32 v68, 0, v80
	v_max_f32_e32 v80, 0, v89
	v_max_f32_e32 v82, v70, v70
	v_max_f32_e32 v83, v71, v71
	v_max_f32_e32 v84, v72, v72
	v_max_f32_e32 v85, v73, v73
	v_max_f32_e32 v90, v69, v69
	v_max_f32_e32 v69, 0, v81
	v_max_f32_e32 v70, 0, v74
	v_max_f32_e32 v71, 0, v75
	v_max_f32_e32 v72, 0, v76
	v_max_f32_e32 v73, 0, v77
	v_max_f32_e32 v74, 0, v82
	v_max_f32_e32 v75, 0, v83
	v_max_f32_e32 v76, 0, v84
	v_max_f32_e32 v77, 0, v85
	v_max_f32_e32 v81, 0, v90
	v_lshlrev_b64 v[84:85], 13, v[98:99]
	v_lshl_add_u64 v[84:85], s[6:7], 0, v[84:85]
	v_or_b32_e32 v82, 64, v106
	v_mov_b32_e32 v83, v107
	v_lshl_add_u64 v[84:85], v[84:85], 0, v[108:109]
	s_waitcnt vmcnt(0) lgkmcnt(0)
	v_fmamk_f32 v86, v86, 0x3a800000, v137
	v_mul_f32_e32 v87, 0x4b800000, v86
	v_cmp_gt_f32_e32 vcc, s43, v86
	s_nop 1
	v_cndmask_b32_e32 v86, v86, v87, vcc
	v_rsq_f32_e32 v88, v86
	v_lshl_add_u64 v[86:87], v[82:83], 2, s[8:9]
	v_mul_f32_e32 v89, 0x45800000, v88
	v_cndmask_b32_e32 v88, v88, v89, vcc
	v_pk_mul_f32 v[66:67], v[66:67], v[88:89] op_sel_hi:[1,0]
	v_pk_mul_f32 v[68:69], v[68:69], v[88:89] op_sel_hi:[1,0]
	v_pk_mul_f32 v[70:71], v[70:71], v[88:89] op_sel_hi:[1,0]
	v_pk_mul_f32 v[72:73], v[72:73], v[88:89] op_sel_hi:[1,0]
	v_pk_mul_f32 v[74:75], v[74:75], v[88:89] op_sel_hi:[1,0]
	v_pk_mul_f32 v[76:77], v[76:77], v[88:89] op_sel_hi:[1,0]
	v_pk_mul_f32 v[78:79], v[78:79], v[88:89] op_sel_hi:[1,0]
	v_pk_mul_f32 v[80:81], v[80:81], v[88:89] op_sel_hi:[1,0]
	v_pk_mul_f32 v[66:67], v[66:67], v[66:67]
	v_pk_mul_f32 v[68:69], v[68:69], v[68:69]
	v_pk_mul_f32 v[70:71], v[70:71], v[70:71]
	v_pk_mul_f32 v[72:73], v[72:73], v[72:73]
	v_pk_mul_f32 v[74:75], v[74:75], v[74:75]
	v_pk_mul_f32 v[76:77], v[76:77], v[76:77]
	v_pk_mul_f32 v[78:79], v[78:79], v[78:79]
	v_pk_mul_f32 v[80:81], v[80:81], v[80:81]
	v_cvt_pk_bf16_f32 v66, v66, v67
	v_cvt_pk_bf16_f32 v67, v68, v69
	v_cvt_pk_bf16_f32 v68, v70, v71
	v_cvt_pk_bf16_f32 v69, v72, v73
	v_cvt_pk_bf16_f32 v70, v74, v75
	v_cvt_pk_bf16_f32 v71, v76, v77
	v_cvt_pk_bf16_f32 v72, v78, v79
	v_cvt_pk_bf16_f32 v73, v80, v81
	v_mbcnt_lo_u32_b32 v242, -1, 0
	v_mbcnt_hi_u32_b32 v242, -1, v242
	v_and_b32_e32 v242, 16, v242
	v_lshrrev_b32_e32 v240, 1, v242
	v_add_u32_e32 v242, v242, v240
	v_mov_b32_e32 v243, 0
	v_lshl_add_u64 v[240:241], v[84:85], 0, v[242:243]
	v_permlane16_swap_b32_e32 v66, v68
	v_permlane16_swap_b32_e32 v67, v69
	v_permlane16_swap_b32_e32 v70, v72
	v_permlane16_swap_b32_e32 v71, v73
	global_store_dwordx4 v[240:241], v[66:69], off
	global_store_dwordx4 v[240:241], v[70:73], off offset:64
	s_nop 1
	flat_load_dword v70, v[86:87]
	v_max_f32_e32 v71, v50, v50
	v_max_f32_e32 v50, 0, v62
	v_max_f32_e32 v62, 0, v71
	v_max_f32_e32 v72, v51, v51
	v_max_f32_e32 v51, 0, v63
	v_max_f32_e32 v63, 0, v72
	v_max_f32_e32 v73, v52, v52
	v_max_f32_e32 v52, 0, v64
	v_max_f32_e32 v64, 0, v73
	v_max_f32_e32 v66, v54, v54
	v_max_f32_e32 v67, v55, v55
	v_max_f32_e32 v68, v56, v56
	v_max_f32_e32 v69, v57, v57
	v_max_f32_e32 v74, v53, v53
	v_max_f32_e32 v53, 0, v65
	v_max_f32_e32 v54, 0, v58
	v_max_f32_e32 v55, 0, v59
	v_max_f32_e32 v56, 0, v60
	v_max_f32_e32 v57, 0, v61
	v_max_f32_e32 v58, 0, v66
	v_max_f32_e32 v59, 0, v67
	v_max_f32_e32 v60, 0, v68
	v_max_f32_e32 v61, 0, v69
	v_max_f32_e32 v65, 0, v74
	v_lshlrev_b64 v[68:69], 13, v[82:83]
	v_lshl_add_u64 v[68:69], s[6:7], 0, v[68:69]
	v_or_b32_e32 v66, 0x50, v106
	v_mov_b32_e32 v67, v107
	v_lshl_add_u64 v[68:69], v[68:69], 0, v[108:109]
	s_waitcnt vmcnt(0) lgkmcnt(0)
	v_fmamk_f32 v70, v70, 0x3a800000, v137
	v_mul_f32_e32 v71, 0x4b800000, v70
	v_cmp_gt_f32_e32 vcc, s43, v70
	s_nop 1
	v_cndmask_b32_e32 v70, v70, v71, vcc
	v_rsq_f32_e32 v72, v70
	v_lshl_add_u64 v[70:71], v[66:67], 2, s[8:9]
	v_mul_f32_e32 v73, 0x45800000, v72
	v_cndmask_b32_e32 v72, v72, v73, vcc
	v_pk_mul_f32 v[50:51], v[50:51], v[72:73] op_sel_hi:[1,0]
	v_pk_mul_f32 v[52:53], v[52:53], v[72:73] op_sel_hi:[1,0]
	v_pk_mul_f32 v[54:55], v[54:55], v[72:73] op_sel_hi:[1,0]
	v_pk_mul_f32 v[56:57], v[56:57], v[72:73] op_sel_hi:[1,0]
	v_pk_mul_f32 v[58:59], v[58:59], v[72:73] op_sel_hi:[1,0]
	v_pk_mul_f32 v[60:61], v[60:61], v[72:73] op_sel_hi:[1,0]
	v_pk_mul_f32 v[62:63], v[62:63], v[72:73] op_sel_hi:[1,0]
	v_pk_mul_f32 v[64:65], v[64:65], v[72:73] op_sel_hi:[1,0]
	v_pk_mul_f32 v[50:51], v[50:51], v[50:51]
	v_pk_mul_f32 v[52:53], v[52:53], v[52:53]
	v_pk_mul_f32 v[54:55], v[54:55], v[54:55]
	v_pk_mul_f32 v[56:57], v[56:57], v[56:57]
	v_pk_mul_f32 v[58:59], v[58:59], v[58:59]
	v_pk_mul_f32 v[60:61], v[60:61], v[60:61]
	v_pk_mul_f32 v[62:63], v[62:63], v[62:63]
	v_pk_mul_f32 v[64:65], v[64:65], v[64:65]
	v_cvt_pk_bf16_f32 v50, v50, v51
	v_cvt_pk_bf16_f32 v51, v52, v53
	v_cvt_pk_bf16_f32 v52, v54, v55
	v_cvt_pk_bf16_f32 v53, v56, v57
	v_cvt_pk_bf16_f32 v54, v58, v59
	v_cvt_pk_bf16_f32 v55, v60, v61
	v_cvt_pk_bf16_f32 v56, v62, v63
	v_cvt_pk_bf16_f32 v57, v64, v65
	v_mbcnt_lo_u32_b32 v242, -1, 0
	v_mbcnt_hi_u32_b32 v242, -1, v242
	v_and_b32_e32 v242, 16, v242
	v_lshrrev_b32_e32 v240, 1, v242
	v_add_u32_e32 v242, v242, v240
	v_mov_b32_e32 v243, 0
	v_lshl_add_u64 v[240:241], v[68:69], 0, v[242:243]
	v_permlane16_swap_b32_e32 v50, v52
	v_permlane16_swap_b32_e32 v51, v53
	v_permlane16_swap_b32_e32 v54, v56
	v_permlane16_swap_b32_e32 v55, v57
	global_store_dwordx4 v[240:241], v[50:53], off
	global_store_dwordx4 v[240:241], v[54:57], off offset:64
	s_nop 1
	flat_load_dword v54, v[70:71]
	v_max_f32_e32 v55, v34, v34
	v_max_f32_e32 v34, 0, v46
	v_max_f32_e32 v46, 0, v55
	v_max_f32_e32 v56, v35, v35
	v_max_f32_e32 v35, 0, v47
	v_max_f32_e32 v47, 0, v56
	v_max_f32_e32 v57, v36, v36
	v_max_f32_e32 v36, 0, v48
	v_max_f32_e32 v48, 0, v57
	v_max_f32_e32 v50, v38, v38
	v_max_f32_e32 v51, v39, v39
	v_max_f32_e32 v52, v40, v40
	v_max_f32_e32 v53, v41, v41
	v_max_f32_e32 v58, v37, v37
	v_max_f32_e32 v37, 0, v49
	v_max_f32_e32 v38, 0, v42
	v_max_f32_e32 v39, 0, v43
	v_max_f32_e32 v40, 0, v44
	v_max_f32_e32 v41, 0, v45
	v_max_f32_e32 v42, 0, v50
	v_max_f32_e32 v43, 0, v51
	v_max_f32_e32 v44, 0, v52
	v_max_f32_e32 v45, 0, v53
	v_max_f32_e32 v49, 0, v58
	v_lshlrev_b64 v[52:53], 13, v[66:67]
	v_lshl_add_u64 v[52:53], s[6:7], 0, v[52:53]
	v_or_b32_e32 v50, 0x60, v106
	v_mov_b32_e32 v51, v107
	v_lshl_add_u64 v[52:53], v[52:53], 0, v[108:109]
	v_or_b32_e32 v106, 0x70, v106
	s_waitcnt vmcnt(0) lgkmcnt(0)
	v_fmamk_f32 v54, v54, 0x3a800000, v137
	v_mul_f32_e32 v55, 0x4b800000, v54
	v_cmp_gt_f32_e32 vcc, s43, v54
	s_nop 1
	v_cndmask_b32_e32 v54, v54, v55, vcc
	v_rsq_f32_e32 v56, v54
	v_lshl_add_u64 v[54:55], v[50:51], 2, s[8:9]
	v_mul_f32_e32 v57, 0x45800000, v56
	v_cndmask_b32_e32 v56, v56, v57, vcc
	v_pk_mul_f32 v[34:35], v[34:35], v[56:57] op_sel_hi:[1,0]
	v_pk_mul_f32 v[36:37], v[36:37], v[56:57] op_sel_hi:[1,0]
	v_pk_mul_f32 v[38:39], v[38:39], v[56:57] op_sel_hi:[1,0]
	v_pk_mul_f32 v[40:41], v[40:41], v[56:57] op_sel_hi:[1,0]
	v_pk_mul_f32 v[42:43], v[42:43], v[56:57] op_sel_hi:[1,0]
	v_pk_mul_f32 v[44:45], v[44:45], v[56:57] op_sel_hi:[1,0]
	v_pk_mul_f32 v[46:47], v[46:47], v[56:57] op_sel_hi:[1,0]
	v_pk_mul_f32 v[48:49], v[48:49], v[56:57] op_sel_hi:[1,0]
	v_pk_mul_f32 v[34:35], v[34:35], v[34:35]
	v_pk_mul_f32 v[36:37], v[36:37], v[36:37]
	v_pk_mul_f32 v[38:39], v[38:39], v[38:39]
	v_pk_mul_f32 v[40:41], v[40:41], v[40:41]
	v_pk_mul_f32 v[42:43], v[42:43], v[42:43]
	v_pk_mul_f32 v[44:45], v[44:45], v[44:45]
	v_pk_mul_f32 v[46:47], v[46:47], v[46:47]
	v_pk_mul_f32 v[48:49], v[48:49], v[48:49]
	v_cvt_pk_bf16_f32 v34, v34, v35
	v_cvt_pk_bf16_f32 v35, v36, v37
	v_cvt_pk_bf16_f32 v36, v38, v39
	v_cvt_pk_bf16_f32 v37, v40, v41
	v_cvt_pk_bf16_f32 v38, v42, v43
	v_cvt_pk_bf16_f32 v39, v44, v45
	v_cvt_pk_bf16_f32 v40, v46, v47
	v_cvt_pk_bf16_f32 v41, v48, v49
	v_mbcnt_lo_u32_b32 v242, -1, 0
	v_mbcnt_hi_u32_b32 v242, -1, v242
	v_and_b32_e32 v242, 16, v242
	v_lshrrev_b32_e32 v240, 1, v242
	v_add_u32_e32 v242, v242, v240
	v_mov_b32_e32 v243, 0
	v_lshl_add_u64 v[240:241], v[52:53], 0, v[242:243]
	v_permlane16_swap_b32_e32 v34, v36
	v_permlane16_swap_b32_e32 v35, v37
	v_permlane16_swap_b32_e32 v38, v40
	v_permlane16_swap_b32_e32 v39, v41
	global_store_dwordx4 v[240:241], v[34:37], off
	global_store_dwordx4 v[240:241], v[38:41], off offset:64
	s_nop 1
	flat_load_dword v36, v[54:55]
	v_max_f32_e32 v37, v24, v24
	v_max_f32_e32 v24, 0, v28
	v_max_f32_e32 v28, 0, v37
	v_max_f32_e32 v38, v25, v25
	v_max_f32_e32 v25, 0, v29
	v_max_f32_e32 v29, 0, v38
	v_max_f32_e32 v39, v18, v18
	v_max_f32_e32 v18, 0, v30
	v_max_f32_e32 v30, 0, v39
	v_max_f32_e32 v34, v22, v22
	v_max_f32_e32 v35, v23, v23
	v_max_f32_e32 v40, v19, v19
	v_max_f32_e32 v41, v20, v20
	v_max_f32_e32 v42, v21, v21
	v_max_f32_e32 v19, 0, v31
	v_max_f32_e32 v20, 0, v32
	v_max_f32_e32 v21, 0, v33
	v_max_f32_e32 v22, 0, v26
	v_max_f32_e32 v23, 0, v27
	v_max_f32_e32 v26, 0, v34
	v_max_f32_e32 v27, 0, v35
	v_max_f32_e32 v31, 0, v40
	v_max_f32_e32 v32, 0, v41
	v_max_f32_e32 v33, 0, v42
	v_lshlrev_b64 v[34:35], 13, v[50:51]
	v_lshl_add_u64 v[34:35], s[6:7], 0, v[34:35]
	v_lshl_add_u64 v[34:35], v[34:35], 0, v[108:109]
	s_waitcnt vmcnt(0) lgkmcnt(0)
	v_fmamk_f32 v36, v36, 0x3a800000, v137
	v_mul_f32_e32 v37, 0x4b800000, v36
	v_cmp_gt_f32_e32 vcc, s43, v36
	s_nop 1
	v_cndmask_b32_e32 v36, v36, v37, vcc
	v_rsq_f32_e32 v38, v36
	v_lshl_add_u64 v[36:37], v[106:107], 2, s[8:9]
	v_mul_f32_e32 v39, 0x45800000, v38
	v_cndmask_b32_e32 v38, v38, v39, vcc
	v_pk_mul_f32 v[18:19], v[18:19], v[38:39] op_sel_hi:[1,0]
	v_pk_mul_f32 v[20:21], v[20:21], v[38:39] op_sel_hi:[1,0]
	v_pk_mul_f32 v[22:23], v[22:23], v[38:39] op_sel_hi:[1,0]
	v_pk_mul_f32 v[24:25], v[24:25], v[38:39] op_sel_hi:[1,0]
	v_pk_mul_f32 v[26:27], v[26:27], v[38:39] op_sel_hi:[1,0]
	v_pk_mul_f32 v[28:29], v[28:29], v[38:39] op_sel_hi:[1,0]
	v_pk_mul_f32 v[30:31], v[30:31], v[38:39] op_sel_hi:[1,0]
	v_pk_mul_f32 v[32:33], v[32:33], v[38:39] op_sel_hi:[1,0]
	v_pk_mul_f32 v[18:19], v[18:19], v[18:19]
	v_pk_mul_f32 v[20:21], v[20:21], v[20:21]
	v_pk_mul_f32 v[22:23], v[22:23], v[22:23]
	v_pk_mul_f32 v[24:25], v[24:25], v[24:25]
	v_pk_mul_f32 v[26:27], v[26:27], v[26:27]
	v_pk_mul_f32 v[28:29], v[28:29], v[28:29]
	v_pk_mul_f32 v[30:31], v[30:31], v[30:31]
	v_pk_mul_f32 v[32:33], v[32:33], v[32:33]
	v_cvt_pk_bf16_f32 v18, v18, v19
	v_cvt_pk_bf16_f32 v19, v20, v21
	v_cvt_pk_bf16_f32 v20, v22, v23
	v_cvt_pk_bf16_f32 v21, v24, v25
	v_cvt_pk_bf16_f32 v22, v26, v27
	v_cvt_pk_bf16_f32 v23, v28, v29
	v_cvt_pk_bf16_f32 v24, v30, v31
	v_cvt_pk_bf16_f32 v25, v32, v33
	v_mbcnt_lo_u32_b32 v242, -1, 0
	v_mbcnt_hi_u32_b32 v242, -1, v242
	v_and_b32_e32 v242, 16, v242
	v_lshrrev_b32_e32 v240, 1, v242
	v_add_u32_e32 v242, v242, v240
	v_mov_b32_e32 v243, 0
	v_lshl_add_u64 v[240:241], v[34:35], 0, v[242:243]
	v_permlane16_swap_b32_e32 v18, v20
	v_permlane16_swap_b32_e32 v19, v21
	v_permlane16_swap_b32_e32 v22, v24
	v_permlane16_swap_b32_e32 v23, v25
	global_store_dwordx4 v[240:241], v[18:21], off
	global_store_dwordx4 v[240:241], v[22:25], off offset:64
	s_nop 1
	flat_load_dword v18, v[36:37]
	v_max_f32_e32 v19, v6, v6
	v_max_f32_e32 v6, 0, v10
	v_max_f32_e32 v10, 0, v19
	v_max_f32_e32 v20, v7, v7
	v_max_f32_e32 v7, 0, v11
	v_max_f32_e32 v11, 0, v20
	v_max_f32_e32 v21, v8, v8
	v_max_f32_e32 v8, 0, v12
	v_max_f32_e32 v12, 0, v21
	v_max_f32_e32 v22, v9, v9
	v_max_f32_e32 v23, v2, v2
	v_max_f32_e32 v24, v3, v3
	v_max_f32_e32 v25, v4, v4
	v_max_f32_e32 v26, v5, v5
	v_max_f32_e32 v2, 0, v14
	v_max_f32_e32 v3, 0, v15
	v_max_f32_e32 v4, 0, v16
	v_max_f32_e32 v5, 0, v17
	v_max_f32_e32 v9, 0, v13
	v_max_f32_e32 v13, 0, v22
	v_max_f32_e32 v14, 0, v23
	v_max_f32_e32 v15, 0, v24
	v_max_f32_e32 v16, 0, v25
	v_max_f32_e32 v17, 0, v26
	s_waitcnt vmcnt(0) lgkmcnt(0)
	v_fmamk_f32 v18, v18, 0x3a800000, v137
	v_mul_f32_e32 v19, 0x4b800000, v18
	v_cmp_gt_f32_e32 vcc, s43, v18
	s_nop 1
	v_cndmask_b32_e32 v18, v18, v19, vcc
	v_rsq_f32_e32 v20, v18
	v_lshlrev_b64 v[18:19], 13, v[106:107]
	v_lshl_add_u64 v[18:19], s[6:7], 0, v[18:19]
	v_lshl_add_u64 v[18:19], v[18:19], 0, v[108:109]
	v_mul_f32_e32 v21, 0x45800000, v20
	v_cndmask_b32_e32 v20, v20, v21, vcc
	v_pk_mul_f32 v[2:3], v[2:3], v[20:21] op_sel_hi:[1,0]
	v_pk_mul_f32 v[4:5], v[4:5], v[20:21] op_sel_hi:[1,0]
	v_pk_mul_f32 v[6:7], v[6:7], v[20:21] op_sel_hi:[1,0]
	v_pk_mul_f32 v[8:9], v[8:9], v[20:21] op_sel_hi:[1,0]
	v_pk_mul_f32 v[10:11], v[10:11], v[20:21] op_sel_hi:[1,0]
	v_pk_mul_f32 v[12:13], v[12:13], v[20:21] op_sel_hi:[1,0]
	v_pk_mul_f32 v[14:15], v[14:15], v[20:21] op_sel_hi:[1,0]
	v_pk_mul_f32 v[16:17], v[16:17], v[20:21] op_sel_hi:[1,0]
	v_pk_mul_f32 v[2:3], v[2:3], v[2:3]
	v_pk_mul_f32 v[4:5], v[4:5], v[4:5]
	v_pk_mul_f32 v[6:7], v[6:7], v[6:7]
	v_pk_mul_f32 v[8:9], v[8:9], v[8:9]
	v_pk_mul_f32 v[10:11], v[10:11], v[10:11]
	v_pk_mul_f32 v[12:13], v[12:13], v[12:13]
	v_pk_mul_f32 v[14:15], v[14:15], v[14:15]
	v_pk_mul_f32 v[16:17], v[16:17], v[16:17]
	v_cvt_pk_bf16_f32 v2, v2, v3
	v_cvt_pk_bf16_f32 v3, v4, v5
	v_cvt_pk_bf16_f32 v4, v6, v7
	v_cvt_pk_bf16_f32 v5, v8, v9
	v_cvt_pk_bf16_f32 v6, v10, v11
	v_cvt_pk_bf16_f32 v7, v12, v13
	v_cvt_pk_bf16_f32 v8, v14, v15
	v_cvt_pk_bf16_f32 v9, v16, v17
	v_mbcnt_lo_u32_b32 v242, -1, 0
	v_mbcnt_hi_u32_b32 v242, -1, v242
	v_and_b32_e32 v242, 16, v242
	v_lshrrev_b32_e32 v240, 1, v242
	v_add_u32_e32 v242, v242, v240
	v_mov_b32_e32 v243, 0
	v_lshl_add_u64 v[240:241], v[18:19], 0, v[242:243]
	v_permlane16_swap_b32_e32 v2, v4
	v_permlane16_swap_b32_e32 v3, v5
	v_permlane16_swap_b32_e32 v6, v8
	v_permlane16_swap_b32_e32 v7, v9
	global_store_dwordx4 v[240:241], v[2:5], off
	global_store_dwordx4 v[240:241], v[6:9], off offset:64
	s_nop 1
	s_cbranch_scc0 .LBB0_563
